# scan stage Y: hoist all LDS reads, single wait, MFMAs back-to-back
# speedup vs baseline: 1.0062x; 1.0062x over previous
.LBB0_411:
	s_or_b64 exec, exec, s[2:3]
	s_waitcnt lgkmcnt(0)
	s_barrier
	v_add_u32_e32 v200, v146, v145
	v_add_u32_e32 v112, v156, v163
	ds_read_b128 v[48:51], v180
	ds_read_b128 v[52:55], v112 offset:62976
	ds_read_b128 v[56:59], v112 offset:64256
	v_add_u32_e32 v113, 0x18d00, v164
	v_add_u32_e32 v114, 0x18d00, v165
	ds_read_b32 v60, v113
	ds_read_b32 v86, v114
	s_and_saveexec_b64 s[2:3], s[56:57]
	s_cbranch_execz .Lsy0_r1
	ds_read_b128 v[62:65], v175
	ds_read_b128 v[66:69], v200
.Lsy0_r1:
	s_or_b64 exec, exec, s[2:3]
	s_and_saveexec_b64 s[2:3], s[46:47]
	s_cbranch_execz .Lsy0_r2
	ds_read_b128 v[70:73], v172
	ds_read_b128 v[74:77], v173 offset:2304
	ds_read_b128 v[78:81], v172 offset:64
	ds_read_b128 v[82:85], v173 offset:2368
.Lsy0_r2:
	s_or_b64 exec, exec, s[2:3]
	s_waitcnt lgkmcnt(2)
	v_mfma_f32_16x16x32_bf16 v[14:17], v[48:51], v[52:55], v[14:17]
	v_mfma_f32_16x16x32_bf16 v[18:21], v[48:51], v[56:59], v[18:21]
	s_and_saveexec_b64 s[2:3], s[56:57]
	s_cbranch_execz .Lsy0_m1
	s_waitcnt lgkmcnt(0)
	v_mfma_f32_16x16x32_bf16 v[22:25], v[62:65], v[66:69], v[22:25]
.Lsy0_m1:
	s_or_b64 exec, exec, s[2:3]
	s_and_saveexec_b64 s[2:3], s[46:47]
	s_cbranch_execz .Lsy0_m2
	s_waitcnt lgkmcnt(2)
	v_mfma_f32_16x16x32_bf16 v[22:25], v[70:73], v[74:77], 0
	s_waitcnt lgkmcnt(0)
	v_mfma_f32_16x16x32_bf16 v[22:25], v[78:81], v[82:85], v[22:25]
.Lsy0_m2:
	s_or_b64 exec, exec, s[2:3]
	s_waitcnt lgkmcnt(0)
	s_nop 1
	v_pk_mul_f32 v[16:17], v[16:17], v[60:61] op_sel_hi:[1,0]
	v_pk_mul_f32 v[14:15], v[14:15], v[60:61] op_sel_hi:[1,0]
	v_pk_mul_f32 v[20:21], v[20:21], v[86:87] op_sel_hi:[1,0]
	v_pk_mul_f32 v[18:19], v[18:19], v[86:87] op_sel_hi:[1,0]
	s_nop 0
	v_cvt_pk_bf16_f32 v88, v14, v195
	v_cvt_pk_bf16_f32 v89, v15, v195
	v_cvt_pk_bf16_f32 v90, v16, v195
	v_cvt_pk_bf16_f32 v91, v17, v195
	v_cvt_pk_bf16_f32 v92, v18, v195
	v_cvt_pk_bf16_f32 v93, v19, v195
	v_cvt_pk_bf16_f32 v94, v20, v195
	v_cvt_pk_bf16_f32 v95, v21, v195
	ds_write_b16 v181, v88
	ds_write_b16 v181, v89 offset:144
	ds_write_b16 v181, v90 offset:288
	ds_write_b16 v181, v91 offset:432
	ds_write_b16 v182, v92
	ds_write_b16 v182, v93 offset:144
	ds_write_b16 v182, v94 offset:288
	ds_write_b16 v182, v95 offset:432
	s_and_saveexec_b64 s[2:3], s[56:57]
	s_cbranch_execz .Lsy0_w1
	ds_write_b128 v179, v[22:25]
.Lsy0_w1:
	s_or_b64 exec, exec, s[2:3]
	s_and_saveexec_b64 s[2:3], s[46:47]
	s_cbranch_execz .LBB0_422
	v_cndmask_b32_e64 v22, 0, v22, s[82:83]
	v_cndmask_b32_e64 v23, 0, v23, s[84:85]
	v_cndmask_b32_e64 v24, 0, v24, s[86:87]
	v_cndmask_b32_e64 v25, 0, v25, s[88:89]
	s_and_saveexec_b64 s[68:69], s[50:51]
	s_xor_b64 s[74:75], exec, s[68:69]
	s_cbranch_execz .LBB0_420
	v_cvt_pk_bf16_f32 v22, v22, v23
	v_cvt_pk_bf16_f32 v23, v24, v25
	s_and_saveexec_b64 s[68:69], s[52:53]
	s_xor_b64 s[68:69], exec, s[68:69]
	ds_write_b64 v148, v[22:23] offset:1216
	s_andn2_saveexec_b64 s[80:81], s[68:69]
	v_add_u32_e32 v24, v150, v147
	v_mov_b32_e32 v194, v195
	ds_write2_b64 v24, v[194:195], v[22:23] offset1:4
	s_or_b64 exec, exec, s[80:81]

.LBB0_440:
	s_or_b64 exec, exec, s[74:75]
	s_waitcnt lgkmcnt(0)
	s_barrier
	s_and_b64 s[24:25], s[46:47], s[2:3]
	ds_read_b128 v[48:51], v180 offset:5120
	ds_read_b128 v[52:55], v170 offset:5120
	ds_read_b128 v[56:59], v170 offset:6400
	v_add_u32_e32 v113, 0x18e00, v164
	v_add_u32_e32 v114, 0x18e00, v165
	ds_read_b32 v60, v113
	ds_read_b32 v86, v114
	s_and_saveexec_b64 s[74:75], s[56:57]
	s_cbranch_execz .Lsy1_r1
	ds_read_b128 v[62:65], v175 offset:5120
	ds_read_b128 v[66:69], v200 offset:1280
.Lsy1_r1:
	s_or_b64 exec, exec, s[74:75]
	s_and_saveexec_b64 s[74:75], s[24:25]
	s_cbranch_execz .Lsy1_r2
	ds_read_b128 v[70:73], v172
	ds_read_b128 v[74:77], v173
	ds_read_b128 v[78:81], v172 offset:64
	ds_read_b128 v[82:85], v173 offset:64
.Lsy1_r2:
	s_or_b64 exec, exec, s[74:75]
	s_waitcnt lgkmcnt(2)
	v_mfma_f32_16x16x32_bf16 v[14:17], v[48:51], v[52:55], v[14:17]
	v_mfma_f32_16x16x32_bf16 v[18:21], v[48:51], v[56:59], v[18:21]
	s_and_saveexec_b64 s[74:75], s[56:57]
	s_cbranch_execz .Lsy1_m1
	s_waitcnt lgkmcnt(0)
	v_mfma_f32_16x16x32_bf16 v[22:25], v[62:65], v[66:69], v[22:25]
.Lsy1_m1:
	s_or_b64 exec, exec, s[74:75]
	s_and_saveexec_b64 s[74:75], s[24:25]
	s_cbranch_execz .Lsy1_m2
	s_waitcnt lgkmcnt(2)
	v_mfma_f32_16x16x32_bf16 v[22:25], v[70:73], v[74:77], 0
	s_waitcnt lgkmcnt(0)
	v_mfma_f32_16x16x32_bf16 v[22:25], v[78:81], v[82:85], v[22:25]
.Lsy1_m2:
	s_or_b64 exec, exec, s[74:75]
	s_waitcnt lgkmcnt(0)
	s_nop 1
	v_pk_mul_f32 v[16:17], v[16:17], v[60:61] op_sel_hi:[1,0]
	v_pk_mul_f32 v[14:15], v[14:15], v[60:61] op_sel_hi:[1,0]
	v_pk_mul_f32 v[20:21], v[20:21], v[86:87] op_sel_hi:[1,0]
	v_pk_mul_f32 v[18:19], v[18:19], v[86:87] op_sel_hi:[1,0]
	s_nop 0
	v_cvt_pk_bf16_f32 v88, v14, v195
	v_cvt_pk_bf16_f32 v89, v15, v195
	v_cvt_pk_bf16_f32 v90, v16, v195
	v_cvt_pk_bf16_f32 v91, v17, v195
	v_cvt_pk_bf16_f32 v92, v18, v195
	v_cvt_pk_bf16_f32 v93, v19, v195
	v_cvt_pk_bf16_f32 v94, v20, v195
	v_cvt_pk_bf16_f32 v95, v21, v195
	ds_write_b16 v181, v88
	ds_write_b16 v181, v89 offset:144
	ds_write_b16 v181, v90 offset:288
	ds_write_b16 v181, v91 offset:432
	ds_write_b16 v182, v92
	ds_write_b16 v182, v93 offset:144
	ds_write_b16 v182, v94 offset:288
	ds_write_b16 v182, v95 offset:432
	s_and_saveexec_b64 s[74:75], s[56:57]
	s_cbranch_execz .Lsy1_w1
	ds_write_b128 v179, v[22:25] offset:4096
.Lsy1_w1:
	s_or_b64 exec, exec, s[74:75]
	s_and_saveexec_b64 s[2:3], s[24:25]
	s_cbranch_execz .LBB0_451
	v_cndmask_b32_e64 v22, 0, v22, s[82:83]
	v_cndmask_b32_e64 v23, 0, v23, s[84:85]
	v_cndmask_b32_e64 v24, 0, v24, s[86:87]
	v_cndmask_b32_e64 v25, 0, v25, s[88:89]
	s_and_saveexec_b64 s[24:25], s[50:51]
	s_xor_b64 s[74:75], exec, s[24:25]
	s_cbranch_execz .LBB0_449
	v_cvt_pk_bf16_f32 v22, v22, v23
	v_cvt_pk_bf16_f32 v23, v24, v25
	s_and_saveexec_b64 s[24:25], s[52:53]
	s_xor_b64 s[68:69], exec, s[24:25]
	ds_write_b64 v149, v[22:23]
	s_andn2_saveexec_b64 s[68:69], s[68:69]
	v_add_u32_e32 v24, v150, v147
	v_mov_b32_e32 v194, v195
	ds_write2_b64 v24, v[194:195], v[22:23] offset1:4
	s_or_b64 exec, exec, s[68:69]
	s_movk_i32 s31, 0x7f
